# batch barriers with a longer spin bound (safety net only)
# speedup vs baseline: 1.0222x; 1.0001x over previous
; __device__ __forceinline__ unsigned xb_ld(unsigned* p)              { return __hip_atomic_load(p, __ATOMIC_RELAXED, __HIP_MEMORY_SCOPE_AGENT); }
; __device__ __forceinline__ unsigned xb_add(unsigned* p, unsigned v) { return __hip_atomic_fetch_add(p, v, __ATOMIC_RELAXED, __HIP_MEMORY_SCOPE_AGENT); }
; #define XB_SPIN(cond, bar) do { unsigned _sp = 0; while (cond) { __builtin_amdgcn_s_sleep(1); \
;     if ((++_sp & 255u) == 0u) { if (xb_ld(&(bar)[XB_TMO])) break; if (_sp > XB_SPIN_CAP) { atomicAdd(&(bar)[XB_TMO], 1u); break; } } } } while (0)
; __device__ __forceinline__ void xcd_barrier(const XcdBarrier& b) {
;     asm volatile("s_waitcnt vmcnt(0)" ::: "memory");
;     __syncthreads();
;     if (threadIdx.x == 0) {
;         unsigned* bar = b.bar;
;         __builtin_amdgcn_s_waitcnt(0);
;         unsigned nloc = b.st[0], nx = b.st[1];
;         if (nloc == 0u) { xcd_barrier_complete(bar, b.x, nloc, nx); b.st[0] = nloc; b.st[1] = nx; }
;         const unsigned old = xb_add(&bar[XB_XSUB(b.x)], 1u);
;         const unsigned gen = old / nloc;
;         if (old + 1u == (gen + 1u) * nloc) {
;             __builtin_amdgcn_fence(__ATOMIC_RELEASE, "agent");
;             asm volatile("s_waitcnt vmcnt(0)" ::: "memory");
;             const unsigned og = xb_add(&bar[XB_TOP], 1u);
;             const unsigned tg = og / nx;
;             if (og + 1u == (tg + 1u) * nx) xb_add(&bar[XB_TOPGEN], 1u);
;             else XB_SPIN(xb_ld(&bar[XB_TOPGEN]) == tg, bar);
;             __builtin_amdgcn_fence(__ATOMIC_ACQUIRE, "agent");
;             xb_add(&bar[XB_XGEN(b.x)], 1u);
;             asm volatile("s_waitcnt vmcnt(0)" ::: "memory");
;         } else {
;             XB_SPIN(xb_ld(&bar[XB_XGEN(b.x)]) == gen, bar);
;             __builtin_amdgcn_fence(__ATOMIC_ACQUIRE, "agent");
;             asm volatile("s_waitcnt vmcnt(0)" ::: "memory");
;         }
;     }
;     __syncthreads();
; }
.Lbbsb_spin:
	global_load_dword v1, v0, s[8:9] sc1
	s_waitcnt vmcnt(0)
	v_readfirstlane_b32 s11, v1
	s_cmp_ge_u32 s11, s6
	s_cbranch_scc1 .Lbbsb_done
	s_add_i32 s10, s10, 1
	s_cmp_lt_u32 s10, 0x40000
	s_cbranch_scc1 .Lbbsb_spin
